# speedup vs baseline: 1.0581x; 1.0581x over previous
; #define MFMA(a, b, c) __builtin_amdgcn_mfma_f32_16x16x32_bf16((a), (b), (c), 0, 0, 0)
; #define ADV() { ga += 32; gb += 32; ck += 32; if (ck == K) { ck = 0; citem += gridDim.x; const int ci_ = citem < total ? citem : total - 1; SETPTR(ci_) } }
; #define WAITSTEP() { if (a2) WAITV(4); else WAITV(3); }
;     ...
;     for (int kt = 0; kt < nk; ++kt) {
;       if (VAR != 1) { const char* base = lds + scur; bf16x8 a[MI], b[4];
; #pragma unroll
;         for (int i = 0; i < 4; ++i) b[i] = *(const bf16x8*)(base + boff + i * 1024);
; #pragma unroll
;         for (int i = 0; i < MI; ++i) a[i] = *(const bf16x8*)(base + aoff + i * 1024);
; #pragma unroll
;         for (int i = 0; i < MI; ++i)
; #pragma unroll
;           for (int j = 0; j < 4; ++j) acc[i][j] = MFMA(a[i], b[j], acc[i][j]);
;         if (VAR != 2) GLDS(snext)
;     ...
;         if (MI == 8) {
;           __builtin_amdgcn_sched_group_barrier(0x100, MI + 4, 0);
; #pragma unroll
;           for (int g = 0; g < 4; ++g) { __builtin_amdgcn_sched_group_barrier(0x008, 7, 0); __builtin_amdgcn_sched_group_barrier(0x010, 1, 0); }
;           __builtin_amdgcn_sched_group_barrier(0x008, 4, 0);
;         } else if (MI == 6) {
;           __builtin_amdgcn_sched_group_barrier(0x100, MI + 4, 0);
; #pragma unroll
;           for (int g = 0; g < 4; ++g) { __builtin_amdgcn_sched_group_barrier(0x008, 5, 0); __builtin_amdgcn_sched_group_barrier(0x010, 1, 0); }
;           __builtin_amdgcn_sched_group_barrier(0x008, 4, 0);
;         }
;     ...
;       }
;       ADV()
;       if (VAR == 2) {} else WAITSTEP()
;       __builtin_amdgcn_s_barrier();
;       scur = (scur == 2 * STAGE) ? 0 : scur + STAGE;
;       snext = (snext == 2 * STAGE) ? 0 : snext + STAGE;
.LBB0_210:
	s_add_i32 s62, s4, 0
	v_add3_u32 v140, s62, v143, v144
	v_add3_u32 v128, s62, v145, v144
	ds_read_b128 v[158:161], v140
	ds_read_b128 v[146:149], v128 offset:16384
	ds_read_b128 v[150:153], v128 offset:17408
	ds_read_b128 v[154:157], v128 offset:18432
	ds_read_b128 v[162:165], v128 offset:19456
	ds_read_b128 v[166:169], v140 offset:1024
	ds_read_b128 v[170:173], v140 offset:2048
	ds_read_b128 v[174:177], v140 offset:3072
	ds_read_b128 v[178:181], v140 offset:4096
	ds_read_b128 v[182:185], v140 offset:5120
	ds_read_b128 v[186:189], v140 offset:6144
	v_add_u32_e32 v128, s5, v142
	ds_read_b128 v[190:193], v140 offset:7168
	s_waitcnt lgkmcnt(10)
	v_mfma_f32_16x16x32_bf16 v[124:127], v[158:161], v[146:149], v[124:127]
	v_readfirstlane_b32 s62, v128
	s_mov_b32 m0, s62
	v_lshl_add_u64 v[140:141], v[136:137], 0, s[50:51]
	s_waitcnt lgkmcnt(9)
	v_mfma_f32_16x16x32_bf16 v[120:123], v[158:161], v[150:153], v[120:123]
	s_add_i32 s8, s8, 32
	s_cmpk_lg_i32 s8, 0x400
	s_waitcnt lgkmcnt(8)
	v_mfma_f32_16x16x32_bf16 v[116:119], v[158:161], v[154:157], v[116:119]
	s_waitcnt lgkmcnt(7)
	v_mfma_f32_16x16x32_bf16 v[112:115], v[158:161], v[162:165], v[112:115]
	v_add_u32_e32 v158, 0x2000, v128
	s_nop 0
	v_readfirstlane_b32 s62, v158
	s_waitcnt lgkmcnt(6)
	v_mfma_f32_16x16x32_bf16 v[108:111], v[166:169], v[146:149], v[108:111]
	v_mfma_f32_16x16x32_bf16 v[104:107], v[166:169], v[150:153], v[104:107]
	v_mfma_f32_16x16x32_bf16 v[100:103], v[166:169], v[154:157], v[100:103]
	global_load_lds_dwordx4 v[136:137], off
	s_mov_b32 m0, s62
	v_mfma_f32_16x16x32_bf16 v[96:99], v[166:169], v[162:165], v[96:99]
	s_waitcnt lgkmcnt(5)
	v_mfma_f32_16x16x32_bf16 v[92:95], v[170:173], v[146:149], v[92:95]
	v_mfma_f32_16x16x32_bf16 v[88:91], v[170:173], v[150:153], v[88:91]
	v_mfma_f32_16x16x32_bf16 v[84:87], v[170:173], v[154:157], v[84:87]
	v_mfma_f32_16x16x32_bf16 v[80:83], v[170:173], v[162:165], v[80:83]
	s_waitcnt lgkmcnt(4)
	v_mfma_f32_16x16x32_bf16 v[76:79], v[174:177], v[146:149], v[76:79]
	v_mfma_f32_16x16x32_bf16 v[72:75], v[174:177], v[150:153], v[72:75]
	global_load_lds_dwordx4 v[140:141], off
	v_add_u32_e32 v140, 0x4000, v128
	v_add_u32_e32 v128, 0x6000, v128
	v_readfirstlane_b32 s62, v140
	s_mov_b32 m0, s62
	v_readfirstlane_b32 s62, v128
	v_mfma_f32_16x16x32_bf16 v[68:71], v[174:177], v[154:157], v[68:71]
	v_lshl_add_u64 v[140:141], v[138:139], 0, s[50:51]
	v_mfma_f32_16x16x32_bf16 v[64:67], v[174:177], v[162:165], v[64:67]
	s_waitcnt lgkmcnt(3)
	v_mfma_f32_16x16x32_bf16 v[60:63], v[178:181], v[146:149], v[60:63]
	v_mfma_f32_16x16x32_bf16 v[56:59], v[178:181], v[150:153], v[56:59]
	v_mfma_f32_16x16x32_bf16 v[52:55], v[178:181], v[154:157], v[52:55]
	v_mfma_f32_16x16x32_bf16 v[48:51], v[178:181], v[162:165], v[48:51]
	s_waitcnt lgkmcnt(2)
	v_mfma_f32_16x16x32_bf16 v[40:43], v[182:185], v[146:149], v[40:43]
	global_load_lds_dwordx4 v[138:139], off
	s_mov_b32 m0, s62
	v_mfma_f32_16x16x32_bf16 v[44:47], v[182:185], v[150:153], v[44:47]
	v_mfma_f32_16x16x32_bf16 v[32:35], v[182:185], v[154:157], v[32:35]
	v_mfma_f32_16x16x32_bf16 v[36:39], v[182:185], v[162:165], v[36:39]
	s_waitcnt lgkmcnt(1)
	v_mfma_f32_16x16x32_bf16 v[24:27], v[186:189], v[146:149], v[24:27]
	v_mfma_f32_16x16x32_bf16 v[28:31], v[186:189], v[150:153], v[28:31]
	v_mfma_f32_16x16x32_bf16 v[16:19], v[186:189], v[154:157], v[16:19]
	v_mfma_f32_16x16x32_bf16 v[20:23], v[186:189], v[162:165], v[20:23]
	global_load_lds_dwordx4 v[140:141], off
	s_waitcnt lgkmcnt(0)
	v_mfma_f32_16x16x32_bf16 v[8:11], v[190:193], v[146:149], v[8:11]
	v_mfma_f32_16x16x32_bf16 v[12:15], v[190:193], v[150:153], v[12:15]
	v_mfma_f32_16x16x32_bf16 v[0:3], v[190:193], v[154:157], v[0:3]
	v_mfma_f32_16x16x32_bf16 v[4:7], v[190:193], v[162:165], v[4:7]
	s_cbranch_scc0 .LBB0_208
	v_lshl_add_u64 v[136:137], v[136:137], 0, 64
	v_lshl_add_u64 v[138:139], v[138:139], 0, 64
	s_branch .LBB0_209

; #define MFMA(a, b, c) __builtin_amdgcn_mfma_f32_16x16x32_bf16((a), (b), (c), 0, 0, 0)
; #define ADV() { ga += 32; gb += 32; ck += 32; if (ck == K) { ck = 0; citem += gridDim.x; const int ci_ = citem < total ? citem : total - 1; SETPTR(ci_) } }
; #define WAITSTEP() { if (a2) WAITV(4); else WAITV(3); }
;     ...
;     for (int kt = 0; kt < nk; ++kt) {
;       if (VAR != 1) { const char* base = lds + scur; bf16x8 a[MI], b[4];
; #pragma unroll
;         for (int i = 0; i < 4; ++i) b[i] = *(const bf16x8*)(base + boff + i * 1024);
; #pragma unroll
;         for (int i = 0; i < MI; ++i) a[i] = *(const bf16x8*)(base + aoff + i * 1024);
; #pragma unroll
;         for (int i = 0; i < MI; ++i)
; #pragma unroll
;           for (int j = 0; j < 4; ++j) acc[i][j] = MFMA(a[i], b[j], acc[i][j]);
;         if (VAR != 2) GLDS(snext)
;     ...
;         if (MI == 8) {
;           __builtin_amdgcn_sched_group_barrier(0x100, MI + 4, 0);
; #pragma unroll
;           for (int g = 0; g < 4; ++g) { __builtin_amdgcn_sched_group_barrier(0x008, 7, 0); __builtin_amdgcn_sched_group_barrier(0x010, 1, 0); }
;           __builtin_amdgcn_sched_group_barrier(0x008, 4, 0);
;         } else if (MI == 6) {
;           __builtin_amdgcn_sched_group_barrier(0x100, MI + 4, 0);
; #pragma unroll
;           for (int g = 0; g < 4; ++g) { __builtin_amdgcn_sched_group_barrier(0x008, 5, 0); __builtin_amdgcn_sched_group_barrier(0x010, 1, 0); }
;           __builtin_amdgcn_sched_group_barrier(0x008, 4, 0);
;         }
;     ...
;       }
;       ADV()
;       if (VAR == 2) {} else WAITSTEP()
;       __builtin_amdgcn_s_barrier();
;       scur = (scur == 2 * STAGE) ? 0 : scur + STAGE;
;       snext = (snext == 2 * STAGE) ? 0 : snext + STAGE;
.LBB0_256:
	s_add_i32 s1, s8, 0
	v_add3_u32 v188, s1, v156, v157
	v_add3_u32 v128, s1, v158, v157
	ds_read_b128 v[152:155], v188
	ds_read_b128 v[140:143], v128 offset:16384
	ds_read_b128 v[144:147], v128 offset:17408
	ds_read_b128 v[148:151], v128 offset:18432
	ds_read_b128 v[160:163], v128 offset:19456
	ds_read_b128 v[164:167], v188 offset:1024
	ds_read_b128 v[168:171], v188 offset:2048
	ds_read_b128 v[172:175], v188 offset:3072
	ds_read_b128 v[176:179], v188 offset:4096
	ds_read_b128 v[180:183], v188 offset:5120
	ds_read_b128 v[184:187], v188 offset:6144
	v_add_u32_e32 v128, s9, v159
	ds_read_b128 v[188:191], v188 offset:7168
	s_waitcnt lgkmcnt(10)
	v_mfma_f32_16x16x32_bf16 v[124:127], v[152:155], v[140:143], v[124:127]
	v_readfirstlane_b32 s1, v128
	s_mov_b32 m0, s1
	s_add_i32 s74, s74, 32
	s_waitcnt lgkmcnt(9)
	v_mfma_f32_16x16x32_bf16 v[120:123], v[152:155], v[144:147], v[120:123]
	s_cmpk_lg_i32 s74, 0x400
	s_waitcnt lgkmcnt(8)
	v_mfma_f32_16x16x32_bf16 v[116:119], v[152:155], v[148:151], v[116:119]
	s_waitcnt lgkmcnt(7)
	v_mfma_f32_16x16x32_bf16 v[112:115], v[152:155], v[160:163], v[112:115]
	v_add_u32_e32 v154, 0x2000, v128
	v_lshl_add_u64 v[152:153], v[136:137], 0, s[50:51]
	v_readfirstlane_b32 s1, v154
	s_waitcnt lgkmcnt(6)
	v_mfma_f32_16x16x32_bf16 v[108:111], v[164:167], v[140:143], v[108:111]
	v_mfma_f32_16x16x32_bf16 v[104:107], v[164:167], v[144:147], v[104:107]
	v_mfma_f32_16x16x32_bf16 v[100:103], v[164:167], v[148:151], v[100:103]
	global_load_lds_dwordx4 v[136:137], off
	s_mov_b32 m0, s1
	v_mfma_f32_16x16x32_bf16 v[96:99], v[164:167], v[160:163], v[96:99]
	s_waitcnt lgkmcnt(5)
	v_mfma_f32_16x16x32_bf16 v[92:95], v[168:171], v[140:143], v[92:95]
	v_mfma_f32_16x16x32_bf16 v[88:91], v[168:171], v[144:147], v[88:91]
	v_mfma_f32_16x16x32_bf16 v[84:87], v[168:171], v[148:151], v[84:87]
	v_mfma_f32_16x16x32_bf16 v[80:83], v[168:171], v[160:163], v[80:83]
	s_waitcnt lgkmcnt(4)
	v_mfma_f32_16x16x32_bf16 v[76:79], v[172:175], v[140:143], v[76:79]
	v_mfma_f32_16x16x32_bf16 v[72:75], v[172:175], v[144:147], v[72:75]
	global_load_lds_dwordx4 v[152:153], off
	v_add_u32_e32 v152, 0x4000, v128
	v_add_u32_e32 v128, 0x6000, v128
	v_readfirstlane_b32 s1, v152
	s_mov_b32 m0, s1
	v_readfirstlane_b32 s1, v128
	v_mfma_f32_16x16x32_bf16 v[68:71], v[172:175], v[148:151], v[68:71]
	v_lshl_add_u64 v[152:153], v[138:139], 0, s[50:51]
	v_mfma_f32_16x16x32_bf16 v[64:67], v[172:175], v[160:163], v[64:67]
	s_waitcnt lgkmcnt(3)
	v_mfma_f32_16x16x32_bf16 v[60:63], v[176:179], v[140:143], v[60:63]
	v_mfma_f32_16x16x32_bf16 v[56:59], v[176:179], v[144:147], v[56:59]
	v_mfma_f32_16x16x32_bf16 v[52:55], v[176:179], v[148:151], v[52:55]
	v_mfma_f32_16x16x32_bf16 v[48:51], v[176:179], v[160:163], v[48:51]
	s_waitcnt lgkmcnt(2)
	v_mfma_f32_16x16x32_bf16 v[40:43], v[180:183], v[140:143], v[40:43]
	global_load_lds_dwordx4 v[138:139], off
	s_mov_b32 m0, s1
	v_mfma_f32_16x16x32_bf16 v[44:47], v[180:183], v[144:147], v[44:47]
	v_mfma_f32_16x16x32_bf16 v[32:35], v[180:183], v[148:151], v[32:35]
	v_mfma_f32_16x16x32_bf16 v[36:39], v[180:183], v[160:163], v[36:39]
	s_waitcnt lgkmcnt(1)
	v_mfma_f32_16x16x32_bf16 v[24:27], v[184:187], v[140:143], v[24:27]
	v_mfma_f32_16x16x32_bf16 v[28:31], v[184:187], v[144:147], v[28:31]
	v_mfma_f32_16x16x32_bf16 v[16:19], v[184:187], v[148:151], v[16:19]
	v_mfma_f32_16x16x32_bf16 v[20:23], v[184:187], v[160:163], v[20:23]
	global_load_lds_dwordx4 v[152:153], off
	s_waitcnt lgkmcnt(0)
	v_mfma_f32_16x16x32_bf16 v[8:11], v[188:191], v[140:143], v[8:11]
	v_mfma_f32_16x16x32_bf16 v[12:15], v[188:191], v[144:147], v[12:15]
	v_mfma_f32_16x16x32_bf16 v[0:3], v[188:191], v[148:151], v[0:3]
	v_mfma_f32_16x16x32_bf16 v[4:7], v[188:191], v[160:163], v[4:7]
	s_cbranch_scc0 .LBB0_254
	v_lshl_add_u64 v[136:137], v[136:137], 0, 64
	v_lshl_add_u64 v[138:139], v[138:139], 0, 64
	s_branch .LBB0_255

; #define MFMA(a, b, c) __builtin_amdgcn_mfma_f32_16x16x32_bf16((a), (b), (c), 0, 0, 0)
; __device__ __forceinline__ void phase_dif_attn(const Params& p, char* lds) {
;     ...
;     for (int kt = 0; kt < ntile; ++kt) {
;       const char* kb = lds + (kt & 1) * BUFB; const char* vbuf = kb + KB;
;       if (kt + 1 < ntile) gload(kt + 1);
;       f32x4 st[2][4];
; #pragma unroll
;       for (int mi = 0; mi < 2; ++mi)
; #pragma unroll
;         for (int n = 0; n < 4; ++n) st[mi][n] = f32x4{0.f, 0.f, 0.f, 0.f};
; #pragma unroll
;       for (int kk = 0; kk < 2; ++kk)
; #pragma unroll
;         for (int n = 0; n < 4; ++n) {
;           bf16x8 ka = *(const bf16x8*)(kb + kk * 4096 + (n * 16 + l15) * 64 + quad * 16);
; #pragma unroll
;           for (int mi = 0; mi < 2; ++mi) st[mi][n] = MFMA(ka, qf[mi][kk], st[mi][n]);
;         }
;       bf16x8 pb[2][2];
; #pragma unroll
;       for (int mi = 0; mi < 2; ++mi) {
;         float mx = -1e30f;
; #pragma unroll
;         for (int n = 0; n < 4; ++n)
; #pragma unroll
;           for (int j = 0; j < 4; ++j) mx = fmaxf(mx, st[mi][n][j]);
;         mx = fmaxf(mx, __shfl_xor(mx, 16)); mx = fmaxf(mx, __shfl_xor(mx, 32));
;         float mnew = mrun[mi], alpha = 1.f;
;         if (!__all(mx - mrun[mi] <= 8.f)) {
;           mnew = fmaxf(mrun[mi], mx);
;           alpha = __builtin_amdgcn_exp2f(mrun[mi] - mnew);
;           mrun[mi] = mnew;
; #pragma unroll
;           for (int dv = 0; dv < 8; ++dv) oacc[mi][dv] *= alpha;
;         }
.LBB0_501:
	s_bitcmp1_b32 s6, 0
	s_cselect_b32 s8, 0x6800, 0
	s_add_i32 s8, s8, 0
	s_cmp_lt_u32 s6, 3
	s_cselect_b32 s9, 8, 13
	s_cselect_b32 s62, s77, 0xffffff00
	s_lshl_b32 s9, s3, s9
	s_add_i32 s62, s62, s9
	s_add_i32 s9, s7, s62
	s_ashr_i32 s62, s9, 6
	s_ashr_i32 s63, s62, 31
	v_add_u32_e32 v80, s9, v127
	s_lshl_b64 s[62:63], s[62:63], 17
	v_ashrrev_i32_e32 v81, 31, v80
	s_add_u32 s62, s1, s62
	v_lshlrev_b64 v[80:81], 11, v[80:81]
	s_addc_u32 s63, s4, s63
	v_lshl_add_u64 v[80:81], v[146:147], 0, v[80:81]
	v_lshl_add_u64 v[84:85], s[62:63], 0, v[134:135]
	v_lshl_add_u64 v[88:89], s[62:63], 0, v[136:137]
	v_add3_u32 v148, s8, v126, v156
	v_add3_u32 v198, s8, v125, v124
	ds_read_b128 v[178:181], v148
	ds_read_b128 v[182:185], v148 offset:1024
	global_load_dwordx4 v[80:83], v[80:81], off
	ds_read_b128 v[186:189], v148 offset:2048
	ds_read_b128 v[190:193], v148 offset:3072
	global_load_dwordx4 v[84:87], v[84:85], off
	ds_read_b128 v[194:197], v148 offset:4096
	ds_read_b128 v[228:231], v148 offset:5120
	global_load_dwordx4 v[88:91], v[88:89], off
	ds_read_b128 v[232:235], v148 offset:6144
	ds_read_b128 v[236:239], v148 offset:7168
	s_waitcnt lgkmcnt(7)
	v_mfma_f32_16x16x32_bf16 v[120:123], v[178:181], v[72:75], 0
	v_mfma_f32_16x16x32_bf16 v[104:107], v[178:181], v[76:79], 0
	s_waitcnt lgkmcnt(6)
	v_mfma_f32_16x16x32_bf16 v[116:119], v[182:185], v[72:75], 0
	v_mfma_f32_16x16x32_bf16 v[100:103], v[182:185], v[76:79], 0
	s_waitcnt lgkmcnt(5)
	v_mfma_f32_16x16x32_bf16 v[112:115], v[186:189], v[72:75], 0
	v_mfma_f32_16x16x32_bf16 v[96:99], v[186:189], v[76:79], 0
	s_waitcnt lgkmcnt(4)
	v_mfma_f32_16x16x32_bf16 v[108:111], v[190:193], v[72:75], 0
	v_mfma_f32_16x16x32_bf16 v[92:95], v[190:193], v[76:79], 0
	s_waitcnt lgkmcnt(3)
	v_mfma_f32_16x16x32_bf16 v[120:123], v[194:197], v[64:67], v[120:123]
	v_mfma_f32_16x16x32_bf16 v[104:107], v[194:197], v[68:71], v[104:107]
	s_waitcnt lgkmcnt(2)
	v_mfma_f32_16x16x32_bf16 v[116:119], v[228:231], v[64:67], v[116:119]
	v_mfma_f32_16x16x32_bf16 v[100:103], v[228:231], v[68:71], v[100:103]
	s_waitcnt lgkmcnt(1)
	v_mfma_f32_16x16x32_bf16 v[112:115], v[232:235], v[64:67], v[112:115]
	v_mfma_f32_16x16x32_bf16 v[96:99], v[232:235], v[68:71], v[96:99]
	s_waitcnt lgkmcnt(0)
	v_mfma_f32_16x16x32_bf16 v[108:111], v[236:239], v[64:67], v[108:111]
	v_mfma_f32_16x16x32_bf16 v[92:95], v[236:239], v[68:71], v[92:95]
	ds_read_b64 v[178:179], v198 offset:8192
	ds_read_b64 v[180:181], v198 offset:8224
	ds_read_b64 v[182:183], v198 offset:8256
	ds_read_b64 v[184:185], v198 offset:8288
	ds_read_b64 v[186:187], v198 offset:10496
	ds_read_b64 v[188:189], v198 offset:10528
	ds_read_b64 v[190:191], v198 offset:10560
	ds_read_b64 v[192:193], v198 offset:10592
	ds_read_b64 v[194:195], v198 offset:12800
	ds_read_b64 v[196:197], v198 offset:12832
	ds_read_b64 v[228:229], v198 offset:12864
	ds_read_b64 v[230:231], v198 offset:12896
	ds_read_b64 v[232:233], v198 offset:15104
	ds_read_b64 v[234:235], v198 offset:15136
	v_max3_f32 v148, v120, s21, v121
	v_max3_f32 v148, v148, v122, v123
	v_max3_f32 v148, v148, v116, v117
	v_max3_f32 v148, v148, v118, v119
	v_max3_f32 v148, v148, v112, v113
	v_max3_f32 v148, v148, v114, v115
	v_max3_f32 v148, v148, v108, v109
	v_max3_f32 v148, v148, v110, v111
	v_sub_f32_e32 v150, v148, v163
	v_cmp_ge_f32_e32 vcc, s22, v150
	v_mov_b32_e32 v150, 1.0
	s_cmp_eq_u64 vcc, exec
	s_cbranch_scc1 .Lattn_m1
	ds_bpermute_b32 v199, v157, v148
	s_waitcnt lgkmcnt(0)
	v_max_f32_e32 v199, v199, v199
	v_max_f32_e32 v148, v148, v199
	ds_bpermute_b32 v199, v158, v148
	s_waitcnt lgkmcnt(0)
	v_max_f32_e32 v199, v199, v199
	v_max_f32_e32 v150, v148, v199
	v_max_f32_e32 v150, v150, v150
	v_max_f32_e32 v166, v163, v163
	v_max_f32_e32 v166, v166, v150
	v_sub_f32_e32 v150, v163, v166
	v_exp_f32_e32 v150, v150
	v_mov_b32_e32 v163, v166
	v_pk_mul_f32 v[62:63], v[62:63], v[150:151] op_sel_hi:[1,0]
	v_pk_mul_f32 v[60:61], v[60:61], v[150:151] op_sel_hi:[1,0]
	v_pk_mul_f32 v[50:51], v[50:51], v[150:151] op_sel_hi:[1,0]
	v_pk_mul_f32 v[48:49], v[48:49], v[150:151] op_sel_hi:[1,0]
	v_pk_mul_f32 v[46:47], v[46:47], v[150:151] op_sel_hi:[1,0]
	v_pk_mul_f32 v[44:45], v[44:45], v[150:151] op_sel_hi:[1,0]
	v_pk_mul_f32 v[38:39], v[38:39], v[150:151] op_sel_hi:[1,0]
	v_pk_mul_f32 v[36:37], v[36:37], v[150:151] op_sel_hi:[1,0]
	v_pk_mul_f32 v[30:31], v[30:31], v[150:151] op_sel_hi:[1,0]
	v_pk_mul_f32 v[28:29], v[28:29], v[150:151] op_sel_hi:[1,0]
	v_pk_mul_f32 v[22:23], v[22:23], v[150:151] op_sel_hi:[1,0]
	v_pk_mul_f32 v[20:21], v[20:21], v[150:151] op_sel_hi:[1,0]
	v_pk_mul_f32 v[14:15], v[14:15], v[150:151] op_sel_hi:[1,0]
	v_pk_mul_f32 v[12:13], v[12:13], v[150:151] op_sel_hi:[1,0]
	v_pk_mul_f32 v[6:7], v[6:7], v[150:151] op_sel_hi:[1,0]
	v_pk_mul_f32 v[4:5], v[4:5], v[150:151] op_sel_hi:[1,0]
; __device__ __forceinline__ unsigned cvtpk(float lo, float hi) { f32x2_t v = {lo, hi}; bf16x2_t r = __builtin_convertvector(v, bf16x2_t); return *reinterpret_cast<unsigned*>(&r); }
; __device__ __forceinline__ void phase_dif_attn(const Params& p, char* lds) {
;     ...
;         float mnew = mrun[mi], alpha = 1.f;
;         if (!__all(mx - mrun[mi] <= 8.f)) {
;           mnew = fmaxf(mrun[mi], mx);
;           alpha = __builtin_amdgcn_exp2f(mrun[mi] - mnew);
;           mrun[mi] = mnew;
; #pragma unroll
;           for (int dv = 0; dv < 8; ++dv) oacc[mi][dv] *= alpha;
;         }
;         float rsum = 0.f;
; #pragma unroll
;         for (int n = 0; n < 4; ++n)
; #pragma unroll
;           for (int j = 0; j < 4; ++j) { float pv = __builtin_amdgcn_exp2f(st[mi][n][j] - mnew); st[mi][n][j] = pv; rsum += pv; }
;         lrun[mi] = lrun[mi] * alpha + rsum;
; #pragma unroll
;         for (int ks = 0; ks < 2; ++ks) {
;           u32x4 v = {cvtpk(st[mi][2 * ks][0], st[mi][2 * ks][1]), cvtpk(st[mi][2 * ks][2], st[mi][2 * ks][3]),
;                      cvtpk(st[mi][2 * ks + 1][0], st[mi][2 * ks + 1][1]), cvtpk(st[mi][2 * ks + 1][2], st[mi][2 * ks + 1][3])};
;           pb[mi][ks] = *reinterpret_cast<bf16x8*>(&v);
;         }
;       }
.Lattn_m1:
	v_max3_f32 v166, v104, s21, v105
	v_max3_f32 v166, v166, v106, v107
	v_max3_f32 v166, v166, v100, v101
	v_max3_f32 v166, v166, v102, v103
	v_max3_f32 v166, v166, v96, v97
	v_max3_f32 v166, v166, v98, v99
	v_max3_f32 v166, v166, v92, v93
	v_max3_f32 v166, v166, v94, v95
	v_sub_f32_e32 v167, v166, v162
	v_cmp_ge_f32_e32 vcc, s22, v167
	v_mov_b32_e32 v148, 1.0
	s_cmp_eq_u64 vcc, exec
	s_cbranch_scc1 .Lattn_exp
	ds_bpermute_b32 v167, v157, v166
	s_waitcnt lgkmcnt(0)
	v_max_f32_e32 v167, v167, v167
	v_max_f32_e32 v166, v166, v167
	ds_bpermute_b32 v167, v158, v166
	s_waitcnt lgkmcnt(0)
	v_max_f32_e32 v167, v167, v167
	v_max_f32_e32 v166, v166, v167
	v_max_f32_e32 v148, v166, v166
	v_max_f32_e32 v166, v162, v162
	v_max_f32_e32 v166, v166, v148
	v_sub_f32_e32 v148, v162, v166
	v_exp_f32_e32 v148, v148
	v_mov_b32_e32 v162, v166
	v_pk_mul_f32 v[58:59], v[58:59], v[148:149] op_sel_hi:[1,0]
	v_pk_mul_f32 v[56:57], v[56:57], v[148:149] op_sel_hi:[1,0]
	v_pk_mul_f32 v[54:55], v[54:55], v[148:149] op_sel_hi:[1,0]
	v_pk_mul_f32 v[52:53], v[52:53], v[148:149] op_sel_hi:[1,0]
	v_pk_mul_f32 v[42:43], v[42:43], v[148:149] op_sel_hi:[1,0]
	v_pk_mul_f32 v[40:41], v[40:41], v[148:149] op_sel_hi:[1,0]
	v_pk_mul_f32 v[34:35], v[34:35], v[148:149] op_sel_hi:[1,0]
	v_pk_mul_f32 v[32:33], v[32:33], v[148:149] op_sel_hi:[1,0]
	v_pk_mul_f32 v[26:27], v[26:27], v[148:149] op_sel_hi:[1,0]
	v_pk_mul_f32 v[24:25], v[24:25], v[148:149] op_sel_hi:[1,0]
	v_pk_mul_f32 v[18:19], v[18:19], v[148:149] op_sel_hi:[1,0]
	v_pk_mul_f32 v[16:17], v[16:17], v[148:149] op_sel_hi:[1,0]
	v_pk_mul_f32 v[10:11], v[10:11], v[148:149] op_sel_hi:[1,0]
	v_pk_mul_f32 v[8:9], v[8:9], v[148:149] op_sel_hi:[1,0]
	v_pk_mul_f32 v[2:3], v[2:3], v[148:149] op_sel_hi:[1,0]
	v_pk_mul_f32 v[0:1], v[0:1], v[148:149] op_sel_hi:[1,0]
.Lattn_exp:
	v_sub_f32_e32 v120, v120, v163
	v_exp_f32_e32 v120, v120
	v_sub_f32_e32 v121, v121, v163
	v_exp_f32_e32 v121, v121
	v_sub_f32_e32 v122, v122, v163
	v_exp_f32_e32 v122, v122
	v_sub_f32_e32 v123, v123, v163
	v_exp_f32_e32 v123, v123
	v_sub_f32_e32 v116, v116, v163
	v_add_f32_e32 v166, 0, v120
	v_exp_f32_e32 v167, v116
	v_sub_f32_e32 v117, v117, v163
	v_sub_f32_e32 v104, v104, v162
	v_add_f32_e32 v166, v121, v166
	v_exp_f32_e32 v117, v117
	v_sub_f32_e32 v118, v118, v163
	v_sub_f32_e32 v119, v119, v163
	v_exp_f32_e32 v104, v104
	v_sub_f32_e32 v105, v105, v162
	v_add_f32_e32 v166, v122, v166
	v_exp_f32_e32 v118, v118
	v_exp_f32_e32 v119, v119
	v_exp_f32_e32 v105, v105
	v_sub_f32_e32 v106, v106, v162
	v_add_f32_e32 v166, v123, v166
	v_sub_f32_e32 v112, v112, v163
	v_exp_f32_e32 v106, v106
	v_sub_f32_e32 v107, v107, v162
	v_add_f32_e32 v116, v167, v166
	v_exp_f32_e32 v166, v112
	v_sub_f32_e32 v113, v113, v163
	v_exp_f32_e32 v107, v107
	v_sub_f32_e32 v100, v100, v162
	v_add_f32_e32 v116, v117, v116
	v_exp_f32_e32 v168, v113
	v_sub_f32_e32 v113, v114, v163
	v_cvt_pk_bf16_f32 v114, v167, v117
	v_add_f32_e32 v117, 0, v104
	v_exp_f32_e32 v100, v100
	v_sub_f32_e32 v101, v101, v162
	v_add_f32_e32 v116, v118, v116
	v_exp_f32_e32 v169, v113
	v_sub_f32_e32 v113, v115, v163
	v_cvt_pk_bf16_f32 v115, v118, v119
	v_add_f32_e32 v117, v105, v117
	v_exp_f32_e32 v118, v101
	v_add_f32_e32 v116, v119, v116
	v_exp_f32_e32 v170, v113
	v_sub_f32_e32 v108, v108, v163
	v_add_f32_e32 v117, v106, v117
	v_sub_f32_e32 v102, v102, v162
	v_add_f32_e32 v112, v166, v116
	v_exp_f32_e32 v171, v108
	v_add_f32_e32 v117, v107, v117
	v_exp_f32_e32 v102, v102
	v_sub_f32_e32 v103, v103, v162
	v_add_f32_e32 v112, v168, v112
	v_add_f32_e32 v117, v100, v117
	v_exp_f32_e32 v103, v103
	v_sub_f32_e32 v96, v96, v162
	v_add_f32_e32 v112, v169, v112
	v_add_f32_e32 v101, v118, v117
	v_exp_f32_e32 v117, v96
	v_sub_f32_e32 v97, v97, v162
	v_add_f32_e32 v112, v170, v112
	v_exp_f32_e32 v119, v97
	v_sub_f32_e32 v97, v98, v162
	v_add_f32_e32 v108, v171, v112
	v_cvt_pk_bf16_f32 v112, v120, v121
	v_add_f32_e32 v101, v102, v101
	v_exp_f32_e32 v120, v97
	v_sub_f32_e32 v97, v99, v162
	v_add_f32_e32 v101, v103, v101
	v_exp_f32_e32 v121, v97
	v_sub_f32_e32 v92, v92, v162
	v_cvt_pk_bf16_f32 v113, v122, v123
	v_add_f32_e32 v96, v117, v101
	v_exp_f32_e32 v122, v92
	v_add_f32_e32 v96, v119, v96
	v_add_f32_e32 v96, v120, v96
	v_cvt_pk_bf16_f32 v98, v100, v118
	v_add_f32_e32 v96, v121, v96
	v_cvt_pk_bf16_f32 v97, v106, v107
	v_add_f32_e32 v92, v122, v96
	v_cvt_pk_bf16_f32 v96, v104, v105
	v_cvt_pk_bf16_f32 v99, v102, v103
	v_sub_f32_e32 v109, v109, v163
	v_exp_f32_e32 v172, v109
	v_sub_f32_e32 v109, v110, v163
	v_exp_f32_e32 v173, v109
	v_sub_f32_e32 v109, v111, v163
	v_exp_f32_e32 v111, v109
	v_add_f32_e32 v108, v172, v108
	v_add_f32_e32 v108, v173, v108
	v_sub_f32_e32 v93, v93, v162
	v_add_f32_e32 v116, v111, v108
	v_exp_f32_e32 v123, v93
	v_sub_f32_e32 v93, v94, v162
	v_fmac_f32_e32 v116, v165, v150
	v_exp_f32_e32 v150, v93
	v_sub_f32_e32 v93, v95, v162
	v_exp_f32_e32 v95, v93
	v_add_f32_e32 v92, v123, v92
	v_add_f32_e32 v92, v150, v92
	v_cvt_pk_bf16_f32 v108, v166, v168
	v_cvt_pk_bf16_f32 v109, v169, v170
	v_cvt_pk_bf16_f32 v110, v171, v172
	v_cvt_pk_bf16_f32 v111, v173, v111
	v_add_f32_e32 v101, v95, v92
	v_cvt_pk_bf16_f32 v92, v117, v119
	v_cvt_pk_bf16_f32 v93, v120, v121
	v_cvt_pk_bf16_f32 v94, v122, v123
	v_cvt_pk_bf16_f32 v95, v150, v95
	s_add_i32 s6, s6, 1
	v_fmac_f32_e32 v101, v164, v148
	s_waitcnt lgkmcnt(12)
; #define MFMA(a, b, c) __builtin_amdgcn_mfma_f32_16x16x32_bf16((a), (b), (c), 0, 0, 0)
; __device__ __forceinline__ void phase_dif_attn(const Params& p, char* lds) {
;     ...
; #pragma unroll
;       for (int dv = 0; dv < 8; ++dv)
; #pragma unroll
;         for (int ks = 0; ks < 2; ++ks) {
;           const char* vp = vbuf + (dv * 16 + l15) * 144 + (ks * 32 + quad * 4) * 2;
;           bf16x4 lo = *(const bf16x4*)vp, hi = *(const bf16x4*)(vp + 32);
;           bf16x8 va = {lo[0], lo[1], lo[2], lo[3], hi[0], hi[1], hi[2], hi[3]};
; #pragma unroll
;           for (int mi = 0; mi < 2; ++mi) oacc[mi][dv] = MFMA(va, pb[mi][ks], oacc[mi][dv]);
;           if (ks == 1 && (dv & 1)) __builtin_amdgcn_sched_barrier(0);
;         }
;       if (kt + 1 < ntile) lwrite((kt + 1) & 1);
;       __syncthreads();
	v_mfma_f32_16x16x32_bf16 v[60:63], v[178:181], v[112:115], v[60:63]
	v_mfma_f32_16x16x32_bf16 v[56:59], v[178:181], v[96:99], v[56:59]
	ds_read_b64 v[236:237], v198 offset:15168
	ds_read_b64 v[238:239], v198 offset:15200
	s_waitcnt lgkmcnt(12)
	v_mfma_f32_16x16x32_bf16 v[60:63], v[182:185], v[108:111], v[60:63]
	v_mfma_f32_16x16x32_bf16 v[56:59], v[182:185], v[92:95], v[56:59]
	ds_read_b64 v[178:179], v198 offset:17408
	ds_read_b64 v[180:181], v198 offset:17440
	s_waitcnt lgkmcnt(12)
	v_mfma_f32_16x16x32_bf16 v[48:51], v[186:189], v[112:115], v[48:51]
	v_mfma_f32_16x16x32_bf16 v[52:55], v[186:189], v[96:99], v[52:55]
	ds_read_b64 v[182:183], v198 offset:17472
	ds_read_b64 v[184:185], v198 offset:17504
	s_waitcnt lgkmcnt(12)
	v_mfma_f32_16x16x32_bf16 v[48:51], v[190:193], v[108:111], v[48:51]
	v_mfma_f32_16x16x32_bf16 v[52:55], v[190:193], v[92:95], v[52:55]
	ds_read_b64 v[186:187], v198 offset:19712
	ds_read_b64 v[188:189], v198 offset:19744
	s_waitcnt lgkmcnt(12)
	v_mfma_f32_16x16x32_bf16 v[44:47], v[194:197], v[112:115], v[44:47]
	v_mfma_f32_16x16x32_bf16 v[40:43], v[194:197], v[96:99], v[40:43]
	ds_read_b64 v[190:191], v198 offset:19776
	ds_read_b64 v[192:193], v198 offset:19808
	s_waitcnt lgkmcnt(12)
	v_mfma_f32_16x16x32_bf16 v[44:47], v[228:231], v[108:111], v[44:47]
	v_mfma_f32_16x16x32_bf16 v[40:43], v[228:231], v[92:95], v[40:43]
	ds_read_b64 v[194:195], v198 offset:22016
	ds_read_b64 v[196:197], v198 offset:22048
	s_waitcnt lgkmcnt(12)
	v_mfma_f32_16x16x32_bf16 v[36:39], v[232:235], v[112:115], v[36:39]
	v_mfma_f32_16x16x32_bf16 v[32:35], v[232:235], v[96:99], v[32:35]
	ds_read_b64 v[228:229], v198 offset:22080
	ds_read_b64 v[230:231], v198 offset:22112
	s_waitcnt lgkmcnt(12)
	v_mfma_f32_16x16x32_bf16 v[36:39], v[236:239], v[108:111], v[36:39]
	v_mfma_f32_16x16x32_bf16 v[32:35], v[236:239], v[92:95], v[32:35]
	ds_read_b64 v[232:233], v198 offset:24320
	ds_read_b64 v[234:235], v198 offset:24352
	s_waitcnt lgkmcnt(12)
	v_mfma_f32_16x16x32_bf16 v[28:31], v[178:181], v[112:115], v[28:31]
	v_mfma_f32_16x16x32_bf16 v[24:27], v[178:181], v[96:99], v[24:27]
	ds_read_b64 v[236:237], v198 offset:24384
	ds_read_b64 v[238:239], v198 offset:24416
	s_waitcnt lgkmcnt(12)
	v_mfma_f32_16x16x32_bf16 v[28:31], v[182:185], v[108:111], v[28:31]
	v_mfma_f32_16x16x32_bf16 v[24:27], v[182:185], v[92:95], v[24:27]
	s_waitcnt lgkmcnt(10)
	v_mfma_f32_16x16x32_bf16 v[20:23], v[186:189], v[112:115], v[20:23]
	v_mfma_f32_16x16x32_bf16 v[16:19], v[186:189], v[96:99], v[16:19]
	s_waitcnt lgkmcnt(8)
	v_mfma_f32_16x16x32_bf16 v[20:23], v[190:193], v[108:111], v[20:23]
	v_mfma_f32_16x16x32_bf16 v[16:19], v[190:193], v[92:95], v[16:19]
	s_waitcnt lgkmcnt(6)
	v_mfma_f32_16x16x32_bf16 v[12:15], v[194:197], v[112:115], v[12:15]
	v_mfma_f32_16x16x32_bf16 v[8:11], v[194:197], v[96:99], v[8:11]
	s_waitcnt lgkmcnt(4)
	v_mfma_f32_16x16x32_bf16 v[12:15], v[228:231], v[108:111], v[12:15]
	v_mfma_f32_16x16x32_bf16 v[8:11], v[228:231], v[92:95], v[8:11]
	s_waitcnt lgkmcnt(2)
	v_mfma_f32_16x16x32_bf16 v[4:7], v[232:235], v[112:115], v[4:7]
	v_mfma_f32_16x16x32_bf16 v[0:3], v[232:235], v[96:99], v[0:3]
	s_waitcnt lgkmcnt(0)
	v_mfma_f32_16x16x32_bf16 v[4:7], v[236:239], v[108:111], v[4:7]
	v_mfma_f32_16x16x32_bf16 v[0:3], v[236:239], v[92:95], v[0:3]
	s_bitcmp1_b32 s6, 0
	s_cselect_b32 s8, 0x6800, 0
	s_add_i32 s8, s8, 0
	v_add_u32_e32 v92, s8, v149
	v_add3_u32 v92, v92, v151, v152
	s_waitcnt vmcnt(2)
	ds_write_b128 v92, v[80:83]
	v_add3_u32 v80, s8, v153, v154
	s_add_i32 s7, s7, 64
	s_waitcnt vmcnt(1)
	ds_write_b128 v80, v[84:87] offset:8192
	v_add3_u32 v80, s8, v155, v154
	s_cmp_eq_u32 s5, s6
	s_waitcnt vmcnt(0)
	ds_write_b128 v80, v[88:91] offset:8192
	s_waitcnt lgkmcnt(0)
	s_barrier
	s_cbranch_scc1 .LBB0_508
	v_mov_b32_e32 v164, v101
	v_mov_b32_e32 v165, v116
	s_branch .LBB0_501

; #define MFMA(a, b, c) __builtin_amdgcn_mfma_f32_16x16x32_bf16((a), (b), (c), 0, 0, 0)
; #define ADV() { ga += 32; gb += 32; ck += 32; if (ck == K) { ck = 0; citem += gridDim.x; const int ci_ = citem < total ? citem : total - 1; SETPTR(ci_) } }
; #define WAITSTEP() { if (a2) WAITV(4); else WAITV(3); }
;     ...
;     for (int kt = 0; kt < nk; ++kt) {
;       if (VAR != 1) { const char* base = lds + scur; bf16x8 a[MI], b[4];
; #pragma unroll
;         for (int i = 0; i < 4; ++i) b[i] = *(const bf16x8*)(base + boff + i * 1024);
; #pragma unroll
;         for (int i = 0; i < MI; ++i) a[i] = *(const bf16x8*)(base + aoff + i * 1024);
; #pragma unroll
;         for (int i = 0; i < MI; ++i)
; #pragma unroll
;           for (int j = 0; j < 4; ++j) acc[i][j] = MFMA(a[i], b[j], acc[i][j]);
;         if (VAR != 2) GLDS(snext)
;     ...
;         if (MI == 8) {
;           __builtin_amdgcn_sched_group_barrier(0x100, MI + 4, 0);
; #pragma unroll
;           for (int g = 0; g < 4; ++g) { __builtin_amdgcn_sched_group_barrier(0x008, 7, 0); __builtin_amdgcn_sched_group_barrier(0x010, 1, 0); }
;           __builtin_amdgcn_sched_group_barrier(0x008, 4, 0);
;         } else if (MI == 6) {
;           __builtin_amdgcn_sched_group_barrier(0x100, MI + 4, 0);
; #pragma unroll
;           for (int g = 0; g < 4; ++g) { __builtin_amdgcn_sched_group_barrier(0x008, 5, 0); __builtin_amdgcn_sched_group_barrier(0x010, 1, 0); }
;           __builtin_amdgcn_sched_group_barrier(0x008, 4, 0);
;         }
;     ...
;       }
;       ADV()
;       if (VAR == 2) {} else WAITSTEP()
;       __builtin_amdgcn_s_barrier();
;       scur = (scur == 2 * STAGE) ? 0 : scur + STAGE;
;       snext = (snext == 2 * STAGE) ? 0 : snext + STAGE;
.LBB0_576:
	s_add_i32 s1, s62, 0
	v_add3_u32 v172, s1, v174, v175
	v_add3_u32 v128, s1, v176, v175
	ds_read_b128 v[152:155], v172
	ds_read_b128 v[140:143], v128 offset:16384
	ds_read_b128 v[144:147], v128 offset:17408
	ds_read_b128 v[148:151], v128 offset:18432
	ds_read_b128 v[156:159], v128 offset:19456
	ds_read_b128 v[160:163], v172 offset:1024
	ds_read_b128 v[164:167], v172 offset:2048
	ds_read_b128 v[168:171], v172 offset:3072
	ds_read_b128 v[178:181], v172 offset:4096
	ds_read_b128 v[182:185], v172 offset:5120
	ds_read_b128 v[186:189], v172 offset:6144
	v_add_u32_e32 v128, s63, v177
	ds_read_b128 v[190:193], v172 offset:7168
	s_waitcnt lgkmcnt(10)
	v_mfma_f32_16x16x32_bf16 v[124:127], v[152:155], v[140:143], v[124:127]
	v_readfirstlane_b32 s1, v128
	s_mov_b32 m0, s1
	s_add_i32 s94, s94, 32
	s_waitcnt lgkmcnt(9)
	v_mfma_f32_16x16x32_bf16 v[120:123], v[152:155], v[144:147], v[120:123]
	s_cmpk_lg_i32 s94, 0x400
	s_waitcnt lgkmcnt(8)
	v_mfma_f32_16x16x32_bf16 v[116:119], v[152:155], v[148:151], v[116:119]
	s_waitcnt lgkmcnt(7)
	v_mfma_f32_16x16x32_bf16 v[112:115], v[152:155], v[156:159], v[112:115]
	v_add_u32_e32 v154, 0x2000, v128
	v_lshl_add_u64 v[152:153], v[136:137], 0, s[50:51]
	v_readfirstlane_b32 s1, v154
	s_waitcnt lgkmcnt(6)
	v_mfma_f32_16x16x32_bf16 v[108:111], v[160:163], v[140:143], v[108:111]
	v_mfma_f32_16x16x32_bf16 v[104:107], v[160:163], v[144:147], v[104:107]
	v_mfma_f32_16x16x32_bf16 v[100:103], v[160:163], v[148:151], v[100:103]
	global_load_lds_dwordx4 v[136:137], off
	s_mov_b32 m0, s1
	v_mfma_f32_16x16x32_bf16 v[96:99], v[160:163], v[156:159], v[96:99]
	s_waitcnt lgkmcnt(5)
	v_mfma_f32_16x16x32_bf16 v[92:95], v[164:167], v[140:143], v[92:95]
	v_mfma_f32_16x16x32_bf16 v[88:91], v[164:167], v[144:147], v[88:91]
	v_mfma_f32_16x16x32_bf16 v[84:87], v[164:167], v[148:151], v[84:87]
	v_mfma_f32_16x16x32_bf16 v[80:83], v[164:167], v[156:159], v[80:83]
	s_waitcnt lgkmcnt(4)
	v_mfma_f32_16x16x32_bf16 v[76:79], v[168:171], v[140:143], v[76:79]
	v_mfma_f32_16x16x32_bf16 v[72:75], v[168:171], v[144:147], v[72:75]
	global_load_lds_dwordx4 v[152:153], off
	v_add_u32_e32 v152, 0x4000, v128
	v_add_u32_e32 v128, 0x6000, v128
	v_readfirstlane_b32 s1, v152
	s_mov_b32 m0, s1
	v_readfirstlane_b32 s1, v128
	v_mfma_f32_16x16x32_bf16 v[68:71], v[168:171], v[148:151], v[68:71]
	v_lshl_add_u64 v[152:153], v[138:139], 0, s[50:51]
	v_mfma_f32_16x16x32_bf16 v[64:67], v[168:171], v[156:159], v[64:67]
	s_waitcnt lgkmcnt(3)
	v_mfma_f32_16x16x32_bf16 v[60:63], v[178:181], v[140:143], v[60:63]
	v_mfma_f32_16x16x32_bf16 v[56:59], v[178:181], v[144:147], v[56:59]
	v_mfma_f32_16x16x32_bf16 v[52:55], v[178:181], v[148:151], v[52:55]
	v_mfma_f32_16x16x32_bf16 v[48:51], v[178:181], v[156:159], v[48:51]
	s_waitcnt lgkmcnt(2)
	v_mfma_f32_16x16x32_bf16 v[40:43], v[182:185], v[140:143], v[40:43]
	global_load_lds_dwordx4 v[138:139], off
	s_mov_b32 m0, s1
	v_mfma_f32_16x16x32_bf16 v[44:47], v[182:185], v[144:147], v[44:47]
	v_mfma_f32_16x16x32_bf16 v[32:35], v[182:185], v[148:151], v[32:35]
	v_mfma_f32_16x16x32_bf16 v[36:39], v[182:185], v[156:159], v[36:39]
	s_waitcnt lgkmcnt(1)
	v_mfma_f32_16x16x32_bf16 v[24:27], v[186:189], v[140:143], v[24:27]
	v_mfma_f32_16x16x32_bf16 v[28:31], v[186:189], v[144:147], v[28:31]
	v_mfma_f32_16x16x32_bf16 v[16:19], v[186:189], v[148:151], v[16:19]
	v_mfma_f32_16x16x32_bf16 v[20:23], v[186:189], v[156:159], v[20:23]
	global_load_lds_dwordx4 v[152:153], off
	s_waitcnt lgkmcnt(0)
	v_mfma_f32_16x16x32_bf16 v[8:11], v[190:193], v[140:143], v[8:11]
	v_mfma_f32_16x16x32_bf16 v[12:15], v[190:193], v[144:147], v[12:15]
	v_mfma_f32_16x16x32_bf16 v[0:3], v[190:193], v[148:151], v[0:3]
	v_mfma_f32_16x16x32_bf16 v[4:7], v[190:193], v[156:159], v[4:7]
	s_cbranch_scc0 .LBB0_574
	v_lshl_add_u64 v[136:137], v[136:137], 0, 64
	v_lshl_add_u64 v[138:139], v[138:139], 0, 64
	s_branch .LBB0_575

; #define MFMA(a, b, c) __builtin_amdgcn_mfma_f32_16x16x32_bf16((a), (b), (c), 0, 0, 0)
; #define ADV() { ga += 32; gb += 32; ck += 32; if (ck == K) { ck = 0; citem += gridDim.x; const int ci_ = citem < total ? citem : total - 1; SETPTR(ci_) } }
; #define WAITSTEP() { if (a2) WAITV(4); else WAITV(3); }
;     ...
;     for (int kt = 0; kt < nk; ++kt) {
;       if (VAR != 1) { const char* base = lds + scur; bf16x8 a[MI], b[4];
; #pragma unroll
;         for (int i = 0; i < 4; ++i) b[i] = *(const bf16x8*)(base + boff + i * 1024);
; #pragma unroll
;         for (int i = 0; i < MI; ++i) a[i] = *(const bf16x8*)(base + aoff + i * 1024);
; #pragma unroll
;         for (int i = 0; i < MI; ++i)
; #pragma unroll
;           for (int j = 0; j < 4; ++j) acc[i][j] = MFMA(a[i], b[j], acc[i][j]);
;         if (VAR != 2) GLDS(snext)
;     ...
;         if (MI == 8) {
;           __builtin_amdgcn_sched_group_barrier(0x100, MI + 4, 0);
; #pragma unroll
;           for (int g = 0; g < 4; ++g) { __builtin_amdgcn_sched_group_barrier(0x008, 7, 0); __builtin_amdgcn_sched_group_barrier(0x010, 1, 0); }
;           __builtin_amdgcn_sched_group_barrier(0x008, 4, 0);
;         } else if (MI == 6) {
;           __builtin_amdgcn_sched_group_barrier(0x100, MI + 4, 0);
; #pragma unroll
;           for (int g = 0; g < 4; ++g) { __builtin_amdgcn_sched_group_barrier(0x008, 5, 0); __builtin_amdgcn_sched_group_barrier(0x010, 1, 0); }
;           __builtin_amdgcn_sched_group_barrier(0x008, 4, 0);
;         }
;     ...
;       }
;       ADV()
;       if (VAR == 2) {} else WAITSTEP()
;       __builtin_amdgcn_s_barrier();
;       scur = (scur == 2 * STAGE) ? 0 : scur + STAGE;
;       snext = (snext == 2 * STAGE) ? 0 : snext + STAGE;
.LBB0_974:
	s_add_i32 s6, s0, 0
	v_add3_u32 v188, s6, v144, v145
	v_add3_u32 v128, s6, v146, v145
	ds_read_b128 v[156:159], v188
	ds_read_b128 v[140:143], v128 offset:16384
	ds_read_b128 v[148:151], v128 offset:17408
	ds_read_b128 v[152:155], v128 offset:18432
	ds_read_b128 v[160:163], v128 offset:19456
	ds_read_b128 v[164:167], v188 offset:1024
	ds_read_b128 v[168:171], v188 offset:2048
	ds_read_b128 v[172:175], v188 offset:3072
	ds_read_b128 v[176:179], v188 offset:4096
	ds_read_b128 v[180:183], v188 offset:5120
	ds_read_b128 v[184:187], v188 offset:6144
	v_add_u32_e32 v128, s1, v147
	ds_read_b128 v[188:191], v188 offset:7168
	s_waitcnt lgkmcnt(10)
	v_mfma_f32_16x16x32_bf16 v[124:127], v[156:159], v[140:143], v[124:127]
	v_readfirstlane_b32 s6, v128
	s_mov_b32 m0, s6
	s_add_i32 s4, s4, 32
	s_waitcnt lgkmcnt(9)
	v_mfma_f32_16x16x32_bf16 v[120:123], v[156:159], v[148:151], v[120:123]
	s_cmpk_lg_i32 s4, 0x400
	s_waitcnt lgkmcnt(8)
	v_mfma_f32_16x16x32_bf16 v[116:119], v[156:159], v[152:155], v[116:119]
	s_waitcnt lgkmcnt(7)
	v_mfma_f32_16x16x32_bf16 v[112:115], v[156:159], v[160:163], v[112:115]
	v_add_u32_e32 v158, 0x2000, v128
	v_lshl_add_u64 v[156:157], v[136:137], 0, s[50:51]
	v_readfirstlane_b32 s6, v158
	s_waitcnt lgkmcnt(6)
	v_mfma_f32_16x16x32_bf16 v[108:111], v[164:167], v[140:143], v[108:111]
	v_mfma_f32_16x16x32_bf16 v[104:107], v[164:167], v[148:151], v[104:107]
	v_mfma_f32_16x16x32_bf16 v[100:103], v[164:167], v[152:155], v[100:103]
	global_load_lds_dwordx4 v[136:137], off
	s_mov_b32 m0, s6
	v_mfma_f32_16x16x32_bf16 v[96:99], v[164:167], v[160:163], v[96:99]
	s_waitcnt lgkmcnt(5)
	v_mfma_f32_16x16x32_bf16 v[92:95], v[168:171], v[140:143], v[92:95]
	v_mfma_f32_16x16x32_bf16 v[88:91], v[168:171], v[148:151], v[88:91]
	v_mfma_f32_16x16x32_bf16 v[84:87], v[168:171], v[152:155], v[84:87]
	v_mfma_f32_16x16x32_bf16 v[80:83], v[168:171], v[160:163], v[80:83]
	s_waitcnt lgkmcnt(4)
	v_mfma_f32_16x16x32_bf16 v[76:79], v[172:175], v[140:143], v[76:79]
	v_mfma_f32_16x16x32_bf16 v[72:75], v[172:175], v[148:151], v[72:75]
	global_load_lds_dwordx4 v[156:157], off
	v_add_u32_e32 v156, 0x4000, v128
	v_add_u32_e32 v128, 0x6000, v128
	v_readfirstlane_b32 s6, v156
	s_mov_b32 m0, s6
	v_readfirstlane_b32 s6, v128
	v_mfma_f32_16x16x32_bf16 v[68:71], v[172:175], v[152:155], v[68:71]
	v_lshl_add_u64 v[156:157], v[138:139], 0, s[50:51]
	v_mfma_f32_16x16x32_bf16 v[64:67], v[172:175], v[160:163], v[64:67]
	s_waitcnt lgkmcnt(3)
	v_mfma_f32_16x16x32_bf16 v[60:63], v[176:179], v[140:143], v[60:63]
	v_mfma_f32_16x16x32_bf16 v[56:59], v[176:179], v[148:151], v[56:59]
	v_mfma_f32_16x16x32_bf16 v[52:55], v[176:179], v[152:155], v[52:55]
	v_mfma_f32_16x16x32_bf16 v[48:51], v[176:179], v[160:163], v[48:51]
	s_waitcnt lgkmcnt(2)
	v_mfma_f32_16x16x32_bf16 v[44:47], v[180:183], v[140:143], v[44:47]
	global_load_lds_dwordx4 v[138:139], off
	s_mov_b32 m0, s6
	v_mfma_f32_16x16x32_bf16 v[40:43], v[180:183], v[148:151], v[40:43]
	v_mfma_f32_16x16x32_bf16 v[36:39], v[180:183], v[152:155], v[36:39]
	v_mfma_f32_16x16x32_bf16 v[32:35], v[180:183], v[160:163], v[32:35]
	s_waitcnt lgkmcnt(1)
	v_mfma_f32_16x16x32_bf16 v[28:31], v[184:187], v[140:143], v[28:31]
	v_mfma_f32_16x16x32_bf16 v[24:27], v[184:187], v[148:151], v[24:27]
	v_mfma_f32_16x16x32_bf16 v[20:23], v[184:187], v[152:155], v[20:23]
	v_mfma_f32_16x16x32_bf16 v[16:19], v[184:187], v[160:163], v[16:19]
	global_load_lds_dwordx4 v[156:157], off
	s_waitcnt lgkmcnt(0)
	v_mfma_f32_16x16x32_bf16 v[12:15], v[188:191], v[140:143], v[12:15]
	v_mfma_f32_16x16x32_bf16 v[8:11], v[188:191], v[148:151], v[8:11]
	v_mfma_f32_16x16x32_bf16 v[4:7], v[188:191], v[152:155], v[4:7]
	v_mfma_f32_16x16x32_bf16 v[0:3], v[188:191], v[160:163], v[0:3]
	s_cbranch_scc0 .LBB0_972
	v_lshl_add_u64 v[136:137], v[136:137], 0, 64
	v_lshl_add_u64 v[138:139], v[138:139], 0, 64
	s_branch .LBB0_973

; #define MFMA(a, b, c) __builtin_amdgcn_mfma_f32_16x16x32_bf16((a), (b), (c), 0, 0, 0)
; #define ADV() { ga += 32; gb += 32; ck += 32; if (ck == K) { ck = 0; citem += gridDim.x; const int ci_ = citem < total ? citem : total - 1; SETPTR(ci_) } }
; #define WAITSTEP() { if (a2) WAITV(4); else WAITV(3); }
;     ...
;     for (int kt = 0; kt < nk; ++kt) {
;       if (VAR != 1) { const char* base = lds + scur; bf16x8 a[MI], b[4];
; #pragma unroll
;         for (int i = 0; i < 4; ++i) b[i] = *(const bf16x8*)(base + boff + i * 1024);
; #pragma unroll
;         for (int i = 0; i < MI; ++i) a[i] = *(const bf16x8*)(base + aoff + i * 1024);
; #pragma unroll
;         for (int i = 0; i < MI; ++i)
; #pragma unroll
;           for (int j = 0; j < 4; ++j) acc[i][j] = MFMA(a[i], b[j], acc[i][j]);
;         if (VAR != 2) GLDS(snext)
;     ...
;         if (MI == 8) {
;           __builtin_amdgcn_sched_group_barrier(0x100, MI + 4, 0);
; #pragma unroll
;           for (int g = 0; g < 4; ++g) { __builtin_amdgcn_sched_group_barrier(0x008, 7, 0); __builtin_amdgcn_sched_group_barrier(0x010, 1, 0); }
;           __builtin_amdgcn_sched_group_barrier(0x008, 4, 0);
;         } else if (MI == 6) {
;           __builtin_amdgcn_sched_group_barrier(0x100, MI + 4, 0);
; #pragma unroll
;           for (int g = 0; g < 4; ++g) { __builtin_amdgcn_sched_group_barrier(0x008, 5, 0); __builtin_amdgcn_sched_group_barrier(0x010, 1, 0); }
;           __builtin_amdgcn_sched_group_barrier(0x008, 4, 0);
;         }
;     ...
;       }
;       ADV()
;       if (VAR == 2) {} else WAITSTEP()
;       __builtin_amdgcn_s_barrier();
;       scur = (scur == 2 * STAGE) ? 0 : scur + STAGE;
;       snext = (snext == 2 * STAGE) ? 0 : snext + STAGE;
.LBB0_1049:
	s_add_i32 s1, s4, 0
	v_add3_u32 v188, s1, v144, v145
	v_add3_u32 v128, s1, v146, v145
	ds_read_b128 v[156:159], v188
	ds_read_b128 v[140:143], v128 offset:16384
	ds_read_b128 v[148:151], v128 offset:17408
	ds_read_b128 v[152:155], v128 offset:18432
	ds_read_b128 v[160:163], v128 offset:19456
	ds_read_b128 v[164:167], v188 offset:1024
	ds_read_b128 v[168:171], v188 offset:2048
	ds_read_b128 v[172:175], v188 offset:3072
	ds_read_b128 v[176:179], v188 offset:4096
	ds_read_b128 v[180:183], v188 offset:5120
	ds_read_b128 v[184:187], v188 offset:6144
	v_add_u32_e32 v128, s5, v147
	ds_read_b128 v[188:191], v188 offset:7168
	s_waitcnt lgkmcnt(10)
	v_mfma_f32_16x16x32_bf16 v[124:127], v[156:159], v[140:143], v[124:127]
	v_readfirstlane_b32 s1, v128
	s_mov_b32 m0, s1
	s_add_i32 s8, s8, 32
	s_waitcnt lgkmcnt(9)
	v_mfma_f32_16x16x32_bf16 v[120:123], v[156:159], v[148:151], v[120:123]
	s_cmpk_lg_i32 s8, 0x400
	s_waitcnt lgkmcnt(8)
	v_mfma_f32_16x16x32_bf16 v[116:119], v[156:159], v[152:155], v[116:119]
	s_waitcnt lgkmcnt(7)
	v_mfma_f32_16x16x32_bf16 v[112:115], v[156:159], v[160:163], v[112:115]
	v_add_u32_e32 v158, 0x2000, v128
	v_lshl_add_u64 v[156:157], v[136:137], 0, s[50:51]
	v_readfirstlane_b32 s1, v158
	s_waitcnt lgkmcnt(6)
	v_mfma_f32_16x16x32_bf16 v[108:111], v[164:167], v[140:143], v[108:111]
	v_mfma_f32_16x16x32_bf16 v[104:107], v[164:167], v[148:151], v[104:107]
	v_mfma_f32_16x16x32_bf16 v[100:103], v[164:167], v[152:155], v[100:103]
	global_load_lds_dwordx4 v[136:137], off
	s_mov_b32 m0, s1
	v_mfma_f32_16x16x32_bf16 v[96:99], v[164:167], v[160:163], v[96:99]
	s_waitcnt lgkmcnt(5)
	v_mfma_f32_16x16x32_bf16 v[92:95], v[168:171], v[140:143], v[92:95]
	v_mfma_f32_16x16x32_bf16 v[88:91], v[168:171], v[148:151], v[88:91]
	v_mfma_f32_16x16x32_bf16 v[84:87], v[168:171], v[152:155], v[84:87]
	v_mfma_f32_16x16x32_bf16 v[80:83], v[168:171], v[160:163], v[80:83]
	s_waitcnt lgkmcnt(4)
	v_mfma_f32_16x16x32_bf16 v[76:79], v[172:175], v[140:143], v[76:79]
	v_mfma_f32_16x16x32_bf16 v[72:75], v[172:175], v[148:151], v[72:75]
	global_load_lds_dwordx4 v[156:157], off
	v_add_u32_e32 v156, 0x4000, v128
	v_add_u32_e32 v128, 0x6000, v128
	v_readfirstlane_b32 s1, v156
	s_mov_b32 m0, s1
	v_readfirstlane_b32 s1, v128
	v_mfma_f32_16x16x32_bf16 v[68:71], v[172:175], v[152:155], v[68:71]
	v_lshl_add_u64 v[156:157], v[138:139], 0, s[50:51]
	v_mfma_f32_16x16x32_bf16 v[64:67], v[172:175], v[160:163], v[64:67]
	s_waitcnt lgkmcnt(3)
	v_mfma_f32_16x16x32_bf16 v[60:63], v[176:179], v[140:143], v[60:63]
	v_mfma_f32_16x16x32_bf16 v[56:59], v[176:179], v[148:151], v[56:59]
	v_mfma_f32_16x16x32_bf16 v[52:55], v[176:179], v[152:155], v[52:55]
	v_mfma_f32_16x16x32_bf16 v[48:51], v[176:179], v[160:163], v[48:51]
	s_waitcnt lgkmcnt(2)
	v_mfma_f32_16x16x32_bf16 v[44:47], v[180:183], v[140:143], v[44:47]
	global_load_lds_dwordx4 v[138:139], off
	s_mov_b32 m0, s1
	v_mfma_f32_16x16x32_bf16 v[40:43], v[180:183], v[148:151], v[40:43]
	v_mfma_f32_16x16x32_bf16 v[36:39], v[180:183], v[152:155], v[36:39]
	v_mfma_f32_16x16x32_bf16 v[32:35], v[180:183], v[160:163], v[32:35]
	s_waitcnt lgkmcnt(1)
	v_mfma_f32_16x16x32_bf16 v[28:31], v[184:187], v[140:143], v[28:31]
	v_mfma_f32_16x16x32_bf16 v[24:27], v[184:187], v[148:151], v[24:27]
	v_mfma_f32_16x16x32_bf16 v[20:23], v[184:187], v[152:155], v[20:23]
	v_mfma_f32_16x16x32_bf16 v[16:19], v[184:187], v[160:163], v[16:19]
	global_load_lds_dwordx4 v[156:157], off
	s_waitcnt lgkmcnt(0)
	v_mfma_f32_16x16x32_bf16 v[12:15], v[188:191], v[140:143], v[12:15]
	v_mfma_f32_16x16x32_bf16 v[8:11], v[188:191], v[148:151], v[8:11]
	v_mfma_f32_16x16x32_bf16 v[4:7], v[188:191], v[152:155], v[4:7]
	v_mfma_f32_16x16x32_bf16 v[0:3], v[188:191], v[160:163], v[0:3]
	s_cbranch_scc0 .LBB0_1047
	v_lshl_add_u64 v[136:137], v[136:137], 0, 64
	v_lshl_add_u64 v[138:139], v[138:139], 0, 64
	s_branch .LBB0_1048

; #define MFMA(a, b, c) __builtin_amdgcn_mfma_f32_16x16x32_bf16((a), (b), (c), 0, 0, 0)
; #define ADV() { ga += 32; gb += 32; ck += 32; if (ck == K) { ck = 0; citem += gridDim.x; const int ci_ = citem < total ? citem : total - 1; SETPTR(ci_) } }
; #define WAITSTEP() { if (a2) WAITV(4); else WAITV(3); }
;     ...
;     for (int kt = 0; kt < nk; ++kt) {
;       if (VAR != 1) { const char* base = lds + scur; bf16x8 a[MI], b[4];
; #pragma unroll
;         for (int i = 0; i < 4; ++i) b[i] = *(const bf16x8*)(base + boff + i * 1024);
; #pragma unroll
;         for (int i = 0; i < MI; ++i) a[i] = *(const bf16x8*)(base + aoff + i * 1024);
; #pragma unroll
;         for (int i = 0; i < MI; ++i)
; #pragma unroll
;           for (int j = 0; j < 4; ++j) acc[i][j] = MFMA(a[i], b[j], acc[i][j]);
;         if (VAR != 2) GLDS(snext)
;     ...
;         if (MI == 8) {
;           __builtin_amdgcn_sched_group_barrier(0x100, MI + 4, 0);
; #pragma unroll
;           for (int g = 0; g < 4; ++g) { __builtin_amdgcn_sched_group_barrier(0x008, 7, 0); __builtin_amdgcn_sched_group_barrier(0x010, 1, 0); }
;           __builtin_amdgcn_sched_group_barrier(0x008, 4, 0);
;         } else if (MI == 6) {
;           __builtin_amdgcn_sched_group_barrier(0x100, MI + 4, 0);
; #pragma unroll
;           for (int g = 0; g < 4; ++g) { __builtin_amdgcn_sched_group_barrier(0x008, 5, 0); __builtin_amdgcn_sched_group_barrier(0x010, 1, 0); }
;           __builtin_amdgcn_sched_group_barrier(0x008, 4, 0);
;         }
;     ...
;       }
;       ADV()
;       if (VAR == 2) {} else WAITSTEP()
;       __builtin_amdgcn_s_barrier();
;       scur = (scur == 2 * STAGE) ? 0 : scur + STAGE;
;       snext = (snext == 2 * STAGE) ? 0 : snext + STAGE;
.LBB0_1761:
	s_add_i32 s5, s62, 0
	v_add3_u32 v107, s5, v111, v112
	v_add3_u32 v106, s5, v113, v112
	ds_read_b128 v[118:121], v107
	ds_read_b128 v[114:117], v106 offset:12288
	ds_read_b128 v[122:125], v106 offset:13312
	ds_read_b128 v[132:135], v106 offset:14336
	ds_read_b128 v[136:139], v106 offset:15360
	ds_read_b128 v[140:143], v107 offset:1024
	ds_read_b128 v[144:147], v107 offset:2048
	ds_read_b128 v[148:151], v107 offset:3072
	ds_read_b128 v[152:155], v107 offset:4096
	ds_read_b128 v[156:159], v107 offset:5120
	s_waitcnt lgkmcnt(8)
	v_mfma_f32_16x16x32_bf16 v[92:95], v[118:121], v[114:117], v[92:95]
	v_lshl_add_u64 v[106:107], v[96:97], 1, v[102:103]
	s_add_i32 s74, s74, 32
	s_cmp_lg_u32 s74, s86
	s_waitcnt lgkmcnt(7)
	v_mfma_f32_16x16x32_bf16 v[88:91], v[118:121], v[122:125], v[88:91]
	s_waitcnt lgkmcnt(6)
	v_mfma_f32_16x16x32_bf16 v[84:87], v[118:121], v[132:135], v[84:87]
	s_waitcnt lgkmcnt(5)
	v_mfma_f32_16x16x32_bf16 v[80:83], v[118:121], v[136:139], v[80:83]
	v_add_u32_e32 v118, s6, v109
	v_add_u32_e32 v119, v118, v110
	v_readfirstlane_b32 s5, v118
	s_mov_b32 m0, s5
	v_readfirstlane_b32 s5, v119
	s_waitcnt lgkmcnt(4)
	v_mfma_f32_16x16x32_bf16 v[76:79], v[140:143], v[114:117], v[76:79]
	global_load_lds_dwordx4 v[102:103], off
	s_mov_b32 m0, s5
	v_mfma_f32_16x16x32_bf16 v[72:75], v[140:143], v[122:125], v[72:75]
	v_mfma_f32_16x16x32_bf16 v[68:71], v[140:143], v[132:135], v[68:71]
	v_mfma_f32_16x16x32_bf16 v[64:67], v[140:143], v[136:139], v[64:67]
	s_waitcnt lgkmcnt(3)
	v_mfma_f32_16x16x32_bf16 v[60:63], v[144:147], v[114:117], v[60:63]
	v_mfma_f32_16x16x32_bf16 v[56:59], v[144:147], v[122:125], v[56:59]
	global_load_lds_dwordx4 v[106:107], off
	v_add_u32_e32 v106, 0x3000, v118
	v_add_u32_e32 v118, 0x5000, v118
	v_readfirstlane_b32 s5, v106
	s_mov_b32 m0, s5
	v_readfirstlane_b32 s5, v118
	v_mfma_f32_16x16x32_bf16 v[52:55], v[144:147], v[132:135], v[52:55]
	v_lshl_add_u64 v[106:107], s[2:3], 1, v[104:105]
	v_mfma_f32_16x16x32_bf16 v[48:51], v[144:147], v[136:139], v[48:51]
	s_waitcnt lgkmcnt(2)
	v_mfma_f32_16x16x32_bf16 v[36:39], v[148:151], v[114:117], v[36:39]
	v_mfma_f32_16x16x32_bf16 v[32:35], v[148:151], v[122:125], v[32:35]
	v_mfma_f32_16x16x32_bf16 v[40:43], v[148:151], v[132:135], v[40:43]
	global_load_lds_dwordx4 v[104:105], off
	s_mov_b32 m0, s5
	v_mfma_f32_16x16x32_bf16 v[44:47], v[148:151], v[136:139], v[44:47]
	s_waitcnt lgkmcnt(1)
	v_mfma_f32_16x16x32_bf16 v[16:19], v[152:155], v[114:117], v[16:19]
	v_mfma_f32_16x16x32_bf16 v[20:23], v[152:155], v[122:125], v[20:23]
	v_mfma_f32_16x16x32_bf16 v[24:27], v[152:155], v[132:135], v[24:27]
	v_mfma_f32_16x16x32_bf16 v[28:31], v[152:155], v[136:139], v[28:31]
	global_load_lds_dwordx4 v[106:107], off
	s_waitcnt lgkmcnt(0)
	v_mfma_f32_16x16x32_bf16 v[0:3], v[156:159], v[114:117], v[0:3]
	v_mfma_f32_16x16x32_bf16 v[4:7], v[156:159], v[122:125], v[4:7]
	v_mfma_f32_16x16x32_bf16 v[8:11], v[156:159], v[132:135], v[8:11]
	v_mfma_f32_16x16x32_bf16 v[12:15], v[156:159], v[136:139], v[12:15]
	s_cbranch_scc0 .LBB0_1759
	v_lshl_add_u64 v[102:103], v[102:103], 0, 64
	v_lshl_add_u64 v[104:105], v[104:105], 0, 64
	s_branch .LBB0_1760
